# SSD full-pass entry: two full drains in front of its first loads removed; attention bias-table build: both pair-trips' loads issued before one wait
# speedup vs baseline: 1.0004x; 1.0004x over previous
.LBB0_431:
	v_mov_b32_e32 v114, v0
	v_readlane_b32 s15, v253, 36
	v_readfirstlane_b32 s14, v114
	s_ashr_i32 s18, s14, 8
	s_ashr_i32 s19, s14, 6
	s_add_i32 s52, s18, s15
	s_load_dwordx2 s[20:21], s[12:13], 0x60
	s_waitcnt lgkmcnt(0)
	s_add_u32 s50, s6, 0x4c0000
	s_addc_u32 s51, s7, 0
	s_add_i32 s16, s52, s36
	s_ashr_i32 s17, s16, 31
	s_lshl_b64 s[16:17], s[16:17], 2
	v_and_b32_e32 v1, 15, v114
	s_add_u32 s16, s20, s16
	s_addc_u32 s17, s21, s17
	s_and_b32 s92, s19, 3
	v_lshlrev_b32_e32 v2, 3, v1
	v_readlane_b32 s15, v253, 30
	s_add_u32 s20, s4, 0xe00000
	s_nop 0
	v_add_u32_e32 v8, 0x200, v114
	s_nop 0
	v_or_b32_e32 v16, s15, v2
	v_readlane_b32 s15, v253, 37
	s_addc_u32 s21, s5, 0
	v_ashrrev_i32_e32 v116, 4, v114
	v_or_b32_e32 v2, s15, v2
	v_readlane_b32 s15, v253, 34
	v_ashrrev_i32_e32 v117, 4, v8
	v_mov_b64_e32 v[4:5], s[20:21]
	v_add_u32_e32 v6, s15, v116
	v_add_u32_e32 v8, s15, v117
	global_load_dword v115, v3, s[16:17]
	v_mad_i64_i32 v[12:13], s[16:17], v6, s95, v[4:5]
	v_lshlrev_b32_e32 v2, 1, v2
	v_mad_i64_i32 v[14:15], s[16:17], v8, s95, v[4:5]
	v_lshlrev_b32_e32 v84, 1, v16
	v_mov_b32_e32 v85, v3
	v_lshl_add_u64 v[6:7], v[12:13], 0, v[2:3]
	v_lshl_add_u64 v[8:9], v[14:15], 0, v[2:3]
	v_lshl_add_u64 v[16:17], v[12:13], 0, v[84:85]
	v_lshl_add_u64 v[24:25], v[14:15], 0, v[84:85]
	global_load_dwordx4 v[4:7], v[6:7], off
	s_nop 0
	global_load_dwordx4 v[8:11], v[8:9], off
	s_nop 0
	global_load_dwordx4 v[12:15], v[16:17], off offset:2048
	s_nop 0
	global_load_dwordx4 v[16:19], v[16:17], off offset:2560
	s_nop 0
	global_load_dwordx4 v[20:23], v[24:25], off offset:2048
	s_nop 0
	global_load_dwordx4 v[24:27], v[24:25], off offset:2560
	s_cmp_lg_u32 s92, 0
	s_cselect_b64 s[24:25], -1, 0
	s_cmp_eq_u32 s92, 0
	v_and_b32_e32 v60, 63, v114
	s_cselect_b64 s[26:27], -1, 0
	v_mov_b32_e32 v118, 0
	s_and_b64 vcc, exec, s[24:25]
	s_cbranch_vccnz .LBB0_433
	v_readlane_b32 s15, v253, 34
	s_ashr_i32 s53, s52, 31
	s_nop 0
	v_or_b32_e32 v28, s15, v60
	v_ashrrev_i32_e32 v29, 31, v28
	v_lshlrev_b64 v[28:29], 6, v[28:29]
	v_lshl_add_u64 v[28:29], s[50:51], 0, v[28:29]
	v_lshl_add_u64 v[28:29], s[52:53], 2, v[28:29]
	global_load_dword v118, v[28:29], off

.LBB0_506:
	s_or_b64 exec, exec, s[20:21]
	v_and_b32_e32 v6, 3, v6
	v_cmp_ne_u32_e32 vcc, 0, v6
	s_and_saveexec_b64 s[20:21], vcc
	s_mov_b32 s26, 0x3fb8aa3b
	s_cbranch_execz .LBB0_509
	v_lshlrev_b32_e32 v7, 11, v9
	v_lshlrev_b32_e32 v8, 2, v74
	v_readlane_b32 s22, v254, 30
	s_nop 1
	v_add3_u32 v7, v7, v8, s22
	s_mov_b64 s[22:23], 0
	v_cmp_ne_u32_e32 vcc, 2, v6
	s_cbranch_vccnz .LBB0_508
	v_ashrrev_i32_e32 v10, 8, v5
	v_ashrrev_i32_e32 v11, 8, v4
	v_lshrrev_b32_e32 v8, 8, v5
	v_lshrrev_b32_e32 v9, 8, v4
	v_and_b32_e32 v10, -4, v10
	v_and_b32_e32 v11, -4, v11
	v_and_b32_e32 v8, 3, v8
	v_and_b32_e32 v9, 3, v9
	v_add_u32_e32 v10, v10, v1
	v_add_u32_e32 v11, v11, v1
	v_or_b32_e32 v8, v10, v8
	v_or_b32_e32 v10, v11, v9
	v_ashrrev_i32_e32 v11, 31, v10
	v_ashrrev_i32_e32 v9, 31, v8
	s_waitcnt lgkmcnt(0)
	v_lshl_add_u64 v[10:11], v[10:11], 2, s[16:17]
	v_lshl_add_u64 v[8:9], v[8:9], 2, s[16:17]
	global_load_dword v170, v[10:11], off
	s_nop 0
	global_load_dword v171, v[8:9], off
	v_add_u32_e32 v176, 0x400, v5
	v_add_u32_e32 v177, 0x400, v4
	v_ashrrev_i32_e32 v178, 8, v176
	v_ashrrev_i32_e32 v179, 8, v177
	v_lshrrev_b32_e32 v180, 8, v176
	v_lshrrev_b32_e32 v181, 8, v177
	v_and_b32_e32 v178, -4, v178
	v_and_b32_e32 v179, -4, v179
	v_and_b32_e32 v180, 3, v180
	v_and_b32_e32 v181, 3, v181
	v_add_u32_e32 v178, v178, v1
	v_add_u32_e32 v179, v179, v1
	v_or_b32_e32 v180, v178, v180
	v_or_b32_e32 v178, v179, v181
	v_ashrrev_i32_e32 v179, 31, v178
	v_ashrrev_i32_e32 v181, 31, v180
	v_lshl_add_u64 v[178:179], v[178:179], 2, s[16:17]
	v_lshl_add_u64 v[180:181], v[180:181], 2, s[16:17]
	global_load_dword v174, v[178:179], off
	s_nop 0
	global_load_dword v175, v[180:181], off
	s_waitcnt vmcnt(0)
	v_pk_mul_f32 v[8:9], v[170:171], s[26:27] op_sel_hi:[1,0]
	v_add_u32_e32 v12, 0xfffff800, v7
	ds_write_b32 v12, v8
	ds_write_b32 v7, v9
	v_add_u32_e32 v7, 0x1000, v7
	v_pk_mul_f32 v[8:9], v[174:175], s[26:27] op_sel_hi:[1,0]
	v_add_u32_e32 v12, 0xfffff800, v7
	s_nop 0
	ds_write_b32 v12, v8
	ds_write_b32 v7, v9
	s_branch .LBB0_509
